# FFN weight conversion: shared software-pipelined routine (3 register sets, 3 LDS buffers, one barrier per tile) replacing compiled convert_w loops at 4 call sites
# baseline (speedup 1.0000x reference)
.Lrw_done:
.LBB0_306:
	s_or_b64 exec, exec, s[40:41]
	v_readlane_b32 s16, v254, 31
	v_readlane_b32 s17, v254, 32
	v_readlane_b32 s66, v254, 35
	v_readlane_b32 s67, v254, 36
	s_nop 1
	s_mov_b64 s[64:65], s[16:17]
	s_cmp_eq_u32 s22, 4
	s_cbranch_scc1 .Lcv_r1
	s_cmp_eq_u32 s22, 13
	s_cbranch_scc1 .Lcv_r2
	s_cmp_eq_u32 s22, 17
	s_cbranch_scc1 .Lcv_r3
	s_branch .Lcv_ret_row
.Lcv_r1:
	v_readlane_b32 s24, v251, 29
	v_readlane_b32 s25, v251, 30
	s_branch .Lcv_rgo
.Lcv_r2:
	v_readlane_b32 s24, v251, 33
	v_readlane_b32 s25, v251, 34
	s_branch .Lcv_rgo
.Lcv_r3:
	v_readlane_b32 s24, v251, 37
	v_readlane_b32 s25, v251, 38
.Lcv_rgo:
	s_mov_b32 s13, 1
	s_nop 3
	s_branch .Lcv_entry
.Lcv_ret_row:
.LBB0_396:
	v_readlane_b32 s48, v254, 37
	s_and_b64 vcc, exec, s[18:19]
	v_readlane_b32 s49, v254, 38
	v_readlane_b32 s52, v254, 41
	v_readlane_b32 s53, v254, 42
	v_readlane_b32 s54, v254, 43
	v_readlane_b32 s55, v254, 44
	v_readlane_b32 s58, v254, 47
	v_readlane_b32 s59, v254, 48
	v_readlane_b32 s60, v254, 49
	v_readlane_b32 s61, v254, 50
	v_readlane_b32 s50, v254, 39
	v_readlane_b32 s51, v254, 40
	v_readlane_b32 s56, v254, 45
	v_readlane_b32 s57, v254, 46
	v_readlane_b32 s62, v254, 51
	v_readlane_b32 s63, v254, 52
	s_cbranch_vccz .LBB0_594
	s_cmp_lg_u32 s22, 0
	s_cbranch_scc1 .LBB0_594
	v_mov_b32_e32 v0, v220
	s_movk_i32 s0, 0x2000
	s_nop 0
	v_cmp_gt_i32_e32 vcc, s0, v0
	s_and_saveexec_b64 s[0:1], vcc
	s_cbranch_execz .LBB0_401
	v_readlane_b32 s76, v251, 39
	v_ashrrev_i32_e32 v1, 31, v0
	v_readlane_b32 s78, v251, 41
	v_readlane_b32 s79, v251, 42
	v_add_u32_e32 v4, 0xfffffe00, v0
	v_lshl_add_u32 v5, v0, 2, 0
	s_movk_i32 s11, 0x7ff
	s_movk_i32 s95, 0x7fff
	v_lshl_add_u64 v[2:3], v[0:1], 2, s[78:79]
	s_mov_b64 s[24:25], 0
	v_readlane_b32 s77, v251, 40
	v_readlane_b32 s80, v251, 43
	v_readlane_b32 s81, v251, 44
	v_readlane_b32 s82, v251, 45
	v_readlane_b32 s83, v251, 46
	v_readlane_b32 s84, v251, 47
	v_readlane_b32 s85, v251, 48
	v_readlane_b32 s86, v251, 49
	v_readlane_b32 s87, v251, 50
	v_readlane_b32 s88, v251, 51
	v_readlane_b32 s89, v251, 52
	v_readlane_b32 s90, v251, 53
	v_readlane_b32 s91, v251, 54

.LBB0_564:
	v_readlane_b32 s24, v251, 51
	v_readlane_b32 s25, v251, 52
	s_mov_b32 s13, 0
	s_nop 3
	s_branch .Lcv_entry
.Lcv_ret_pro:
	v_readlane_b32 s76, v251, 39
	v_readlane_b32 s77, v251, 40
	v_readlane_b32 s78, v251, 41
	v_readlane_b32 s79, v251, 42
	v_readlane_b32 s80, v251, 43
	v_readlane_b32 s81, v251, 44
	v_readlane_b32 s82, v251, 45
	v_readlane_b32 s83, v251, 46
	v_readlane_b32 s84, v251, 47
	v_readlane_b32 s85, v251, 48
	v_readlane_b32 s86, v251, 49
	v_readlane_b32 s87, v251, 50
	v_readlane_b32 s88, v251, 51
	v_readlane_b32 s89, v251, 52
	v_readlane_b32 s90, v251, 53
	v_readlane_b32 s91, v251, 54
	s_movk_i32 s95, 0x7fff
	s_movk_i32 s11, 0x7ff

.Lcv_entry:
	s_add_u32 s28, s20, 0x4000
	s_addc_u32 s29, s21, 0
	v_lshrrev_b32_e32 v38, 3, v220
	v_and_b32_e32 v39, 7, v220
	v_lshlrev_b32_e32 v39, 3, v39
	s_mov_b32 s0, 5632
	v_mul_lo_u32 v36, v38, s0
	v_add_lshl_u32 v36, v36, v39, 2
	s_mov_b32 s0, 1024
	v_mul_lo_u32 v37, v38, s0
	v_add_lshl_u32 v37, v37, v39, 1
	s_movk_i32 s0, 65
	v_mul_lo_u32 v40, v39, s0
	v_add_lshl_u32 v40, v40, v38, 2
	v_mul_lo_u32 v38, v38, s0
	v_add_lshl_u32 v38, v38, v39, 2
	v_mov_b32_e32 v39, v40
	v_add_u32_e32 v40, 1040, v39
	s_mov_b32 s7, s2
	s_cmp_lt_u32 s7, 1408
	s_cbranch_scc0 .Lcv_gu_end
	s_and_b32 s0, s7, 15
	s_lshr_b32 s1, s7, 4
	s_mul_i32 s9, s0, 360448
	s_lshr_b32 s10, s1, 2
	s_lshl_b32 s10, s10, 7
	s_add_i32 s9, s9, s10
	s_and_b32 s10, s1, 1
	s_lshl_b32 s10, s10, 6
	s_add_i32 s9, s9, s10
	s_bitcmp1_b32 s1, 1
	s_cselect_b32 s10, 2816, 0
	s_add_i32 s9, s9, s10
	s_lshl_b32 s9, s9, 2
	s_add_u32 s38, s24, s9
	s_addc_u32 s39, s25, 0
	global_load_dwordx4 v[0:3], v36, s[38:39]
	global_load_dwordx4 v[4:7], v36, s[38:39] offset:16
	s_add_i32 s5, s7, s94
	s_cmp_lt_u32 s5, 1408
	s_cbranch_scc0 .Lcv_gu_loop
	s_and_b32 s0, s5, 15
	s_lshr_b32 s1, s5, 4
	s_mul_i32 s9, s0, 360448
	s_lshr_b32 s10, s1, 2
	s_lshl_b32 s10, s10, 7
	s_add_i32 s9, s9, s10
	s_and_b32 s10, s1, 1
	s_lshl_b32 s10, s10, 6
	s_add_i32 s9, s9, s10
	s_bitcmp1_b32 s1, 1
	s_cselect_b32 s10, 2816, 0
	s_add_i32 s9, s9, s10
	s_lshl_b32 s9, s9, 2
	s_add_u32 s38, s24, s9
	s_addc_u32 s39, s25, 0
	global_load_dwordx4 v[8:11], v36, s[38:39]
	global_load_dwordx4 v[12:15], v36, s[38:39] offset:16
.Lcv_gu_loop:
	s_lshl_b32 s5, s94, 1
	s_add_i32 s5, s5, s7
	s_cmp_lt_u32 s5, 1408
	s_cbranch_scc0 .Lcv_gu_ni0
	s_and_b32 s0, s5, 15
	s_lshr_b32 s1, s5, 4
	s_mul_i32 s9, s0, 360448
	s_lshr_b32 s10, s1, 2
	s_lshl_b32 s10, s10, 7
	s_add_i32 s9, s9, s10
	s_and_b32 s10, s1, 1
	s_lshl_b32 s10, s10, 6
	s_add_i32 s9, s9, s10
	s_bitcmp1_b32 s1, 1
	s_cselect_b32 s10, 2816, 0
	s_add_i32 s9, s9, s10
	s_lshl_b32 s9, s9, 2
	s_add_u32 s38, s24, s9
	s_addc_u32 s39, s25, 0
	global_load_dwordx4 v[16:19], v36, s[38:39]
	global_load_dwordx4 v[20:23], v36, s[38:39] offset:16
	s_waitcnt vmcnt(4)
	s_branch .Lcv_gu_go0

.Lcv_gu_go0:
	ds_write2_b32 v38, v0, v1 offset0:0 offset1:1
	ds_write2_b32 v38, v2, v3 offset0:2 offset1:3
	ds_write2_b32 v38, v4, v5 offset0:4 offset1:5
	ds_write2_b32 v38, v6, v7 offset0:6 offset1:7
	s_waitcnt lgkmcnt(0)
	s_barrier
	ds_read2_b32 v[28:29], v39 offset1:65
	ds_read2_b32 v[30:31], v39 offset0:130 offset1:195
	ds_read2_b32 v[32:33], v40 offset1:65
	ds_read2_b32 v[34:35], v40 offset0:130 offset1:195
	s_and_b32 s0, s7, 15
	s_lshr_b32 s1, s7, 4
	s_lshl_b32 s1, s1, 16
	s_lshl_b32 s0, s0, 6
	s_add_i32 s1, s1, s0
	s_lshl_b32 s1, s1, 1
	s_add_u32 s40, s28, s1
	s_addc_u32 s41, s29, 0
	s_waitcnt lgkmcnt(2)
	v_cvt_pk_bf16_f32 v24, v28, v29
	v_cvt_pk_bf16_f32 v25, v30, v31
	s_waitcnt lgkmcnt(0)
	v_cvt_pk_bf16_f32 v26, v32, v33
	v_cvt_pk_bf16_f32 v27, v34, v35
	global_store_dwordx4 v37, v[24:27], s[40:41]
	s_add_i32 s7, s7, s94
	s_cmp_lt_u32 s7, 1408
	s_cbranch_scc0 .Lcv_gu_end
	v_add_u32_e32 v38, 16640, v38
	v_add_u32_e32 v39, 16640, v39
	v_add_u32_e32 v40, 16640, v40
	s_lshl_b32 s5, s94, 1
	s_add_i32 s5, s5, s7
	s_cmp_lt_u32 s5, 1408
	s_cbranch_scc0 .Lcv_gu_ni1
	s_and_b32 s0, s5, 15
	s_lshr_b32 s1, s5, 4
	s_mul_i32 s9, s0, 360448
	s_lshr_b32 s10, s1, 2
	s_lshl_b32 s10, s10, 7
	s_add_i32 s9, s9, s10
	s_and_b32 s10, s1, 1
	s_lshl_b32 s10, s10, 6
	s_add_i32 s9, s9, s10
	s_bitcmp1_b32 s1, 1
	s_cselect_b32 s10, 2816, 0
	s_add_i32 s9, s9, s10
	s_lshl_b32 s9, s9, 2
	s_add_u32 s38, s24, s9
	s_addc_u32 s39, s25, 0
	global_load_dwordx4 v[0:3], v36, s[38:39]
	global_load_dwordx4 v[4:7], v36, s[38:39] offset:16
	s_waitcnt vmcnt(4)
	s_branch .Lcv_gu_go1

.Lcv_gu_go1:
	ds_write2_b32 v38, v8, v9 offset0:0 offset1:1
	ds_write2_b32 v38, v10, v11 offset0:2 offset1:3
	ds_write2_b32 v38, v12, v13 offset0:4 offset1:5
	ds_write2_b32 v38, v14, v15 offset0:6 offset1:7
	s_waitcnt lgkmcnt(0)
	s_barrier
	ds_read2_b32 v[28:29], v39 offset1:65
	ds_read2_b32 v[30:31], v39 offset0:130 offset1:195
	ds_read2_b32 v[32:33], v40 offset1:65
	ds_read2_b32 v[34:35], v40 offset0:130 offset1:195
	s_and_b32 s0, s7, 15
	s_lshr_b32 s1, s7, 4
	s_lshl_b32 s1, s1, 16
	s_lshl_b32 s0, s0, 6
	s_add_i32 s1, s1, s0
	s_lshl_b32 s1, s1, 1
	s_add_u32 s40, s28, s1
	s_addc_u32 s41, s29, 0
	s_waitcnt lgkmcnt(2)
	v_cvt_pk_bf16_f32 v24, v28, v29
	v_cvt_pk_bf16_f32 v25, v30, v31
	s_waitcnt lgkmcnt(0)
	v_cvt_pk_bf16_f32 v26, v32, v33
	v_cvt_pk_bf16_f32 v27, v34, v35
	global_store_dwordx4 v37, v[24:27], s[40:41]
	s_add_i32 s7, s7, s94
	s_cmp_lt_u32 s7, 1408
	s_cbranch_scc0 .Lcv_gu_end
	v_add_u32_e32 v38, 16640, v38
	v_add_u32_e32 v39, 16640, v39
	v_add_u32_e32 v40, 16640, v40
	s_lshl_b32 s5, s94, 1
	s_add_i32 s5, s5, s7
	s_cmp_lt_u32 s5, 1408
	s_cbranch_scc0 .Lcv_gu_ni2
	s_and_b32 s0, s5, 15
	s_lshr_b32 s1, s5, 4
	s_mul_i32 s9, s0, 360448
	s_lshr_b32 s10, s1, 2
	s_lshl_b32 s10, s10, 7
	s_add_i32 s9, s9, s10
	s_and_b32 s10, s1, 1
	s_lshl_b32 s10, s10, 6
	s_add_i32 s9, s9, s10
	s_bitcmp1_b32 s1, 1
	s_cselect_b32 s10, 2816, 0
	s_add_i32 s9, s9, s10
	s_lshl_b32 s9, s9, 2
	s_add_u32 s38, s24, s9
	s_addc_u32 s39, s25, 0
	global_load_dwordx4 v[8:11], v36, s[38:39]
	global_load_dwordx4 v[12:15], v36, s[38:39] offset:16
	s_waitcnt vmcnt(4)
	s_branch .Lcv_gu_go2

.Lcv_gu_go2:
	ds_write2_b32 v38, v16, v17 offset0:0 offset1:1
	ds_write2_b32 v38, v18, v19 offset0:2 offset1:3
	ds_write2_b32 v38, v20, v21 offset0:4 offset1:5
	ds_write2_b32 v38, v22, v23 offset0:6 offset1:7
	s_waitcnt lgkmcnt(0)
	s_barrier
	ds_read2_b32 v[28:29], v39 offset1:65
	ds_read2_b32 v[30:31], v39 offset0:130 offset1:195
	ds_read2_b32 v[32:33], v40 offset1:65
	ds_read2_b32 v[34:35], v40 offset0:130 offset1:195
	s_and_b32 s0, s7, 15
	s_lshr_b32 s1, s7, 4
	s_lshl_b32 s1, s1, 16
	s_lshl_b32 s0, s0, 6
	s_add_i32 s1, s1, s0
	s_lshl_b32 s1, s1, 1
	s_add_u32 s40, s28, s1
	s_addc_u32 s41, s29, 0
	s_waitcnt lgkmcnt(2)
	v_cvt_pk_bf16_f32 v24, v28, v29
	v_cvt_pk_bf16_f32 v25, v30, v31
	s_waitcnt lgkmcnt(0)
	v_cvt_pk_bf16_f32 v26, v32, v33
	v_cvt_pk_bf16_f32 v27, v34, v35
	global_store_dwordx4 v37, v[24:27], s[40:41]
	s_add_i32 s7, s7, s94
	s_cmp_lt_u32 s7, 1408
	s_cbranch_scc0 .Lcv_gu_end
	v_subrev_u32_e32 v38, 33280, v38
	v_subrev_u32_e32 v39, 33280, v39
	v_subrev_u32_e32 v40, 33280, v40
	s_branch .Lcv_gu_loop
.Lcv_gu_end:
	s_barrier
	s_cmp_eq_u32 s13, 0
	s_cbranch_scc1 .Lcv_d0
	s_cmp_eq_u32 s22, 4
	s_cbranch_scc1 .Lcv_d1
	s_cmp_eq_u32 s22, 13
	s_cbranch_scc1 .Lcv_d2
	v_readlane_b32 s24, v251, 55
	v_readlane_b32 s25, v251, 56
	s_branch .Lcv_dgo
.Lcv_d0:
	v_readlane_b32 s24, v251, 53
	v_readlane_b32 s25, v251, 54
	s_branch .Lcv_dgo
.Lcv_d1:
	v_readlane_b32 s24, v251, 31
	v_readlane_b32 s25, v251, 32
	s_branch .Lcv_dgo
.Lcv_d2:
	v_readlane_b32 s24, v251, 35
	v_readlane_b32 s25, v251, 36
.Lcv_dgo:
	s_add_u32 s28, s20, 0xb04000
	s_addc_u32 s29, s21, 0
	v_lshrrev_b32_e32 v38, 3, v220
	v_and_b32_e32 v39, 7, v220
	v_lshlrev_b32_e32 v39, 3, v39
	s_mov_b32 s0, 1024
	v_mul_lo_u32 v36, v38, s0
	v_add_lshl_u32 v36, v36, v39, 2
	s_mov_b32 s0, 2816
	v_mul_lo_u32 v37, v38, s0
	v_add_lshl_u32 v37, v37, v39, 1
	s_movk_i32 s0, 65
	v_mul_lo_u32 v40, v39, s0
	v_add_lshl_u32 v40, v40, v38, 2
	v_mul_lo_u32 v38, v38, s0
	v_add_lshl_u32 v38, v38, v39, 2
	v_mov_b32_e32 v39, v40
	v_add_u32_e32 v40, 1040, v39
	s_mov_b32 s7, s2
	s_cmp_lt_u32 s7, 704
	s_cbranch_scc0 .Lcv_dn_end
	s_mul_i32 s1, s7, 47663
	s_lshr_b32 s1, s1, 21
	s_mul_i32 s0, s1, 44
	s_sub_i32 s0, s7, s0
	s_lshl_b32 s9, s0, 16
	s_lshl_b32 s10, s1, 6
	s_add_i32 s9, s9, s10
	s_lshl_b32 s9, s9, 2
	s_add_u32 s38, s24, s9
	s_addc_u32 s39, s25, 0
	global_load_dwordx4 v[0:3], v36, s[38:39]
	global_load_dwordx4 v[4:7], v36, s[38:39] offset:16
	s_add_i32 s5, s7, s94
	s_cmp_lt_u32 s5, 704
	s_cbranch_scc0 .Lcv_dn_loop
	s_mul_i32 s1, s5, 47663
	s_lshr_b32 s1, s1, 21
	s_mul_i32 s0, s1, 44
	s_sub_i32 s0, s5, s0
	s_lshl_b32 s9, s0, 16
	s_lshl_b32 s10, s1, 6
	s_add_i32 s9, s9, s10
	s_lshl_b32 s9, s9, 2
	s_add_u32 s38, s24, s9
	s_addc_u32 s39, s25, 0
	global_load_dwordx4 v[8:11], v36, s[38:39]
	global_load_dwordx4 v[12:15], v36, s[38:39] offset:16
.Lcv_dn_loop:
	s_lshl_b32 s5, s94, 1
	s_add_i32 s5, s5, s7
	s_cmp_lt_u32 s5, 704
	s_cbranch_scc0 .Lcv_dn_ni0
	s_mul_i32 s1, s5, 47663
	s_lshr_b32 s1, s1, 21
	s_mul_i32 s0, s1, 44
	s_sub_i32 s0, s5, s0
	s_lshl_b32 s9, s0, 16
	s_lshl_b32 s10, s1, 6
	s_add_i32 s9, s9, s10
	s_lshl_b32 s9, s9, 2
	s_add_u32 s38, s24, s9
	s_addc_u32 s39, s25, 0
	global_load_dwordx4 v[16:19], v36, s[38:39]
	global_load_dwordx4 v[20:23], v36, s[38:39] offset:16
	s_waitcnt vmcnt(4)
	s_branch .Lcv_dn_go0

.Lcv_dn_go0:
	ds_write2_b32 v38, v0, v1 offset0:0 offset1:1
	ds_write2_b32 v38, v2, v3 offset0:2 offset1:3
	ds_write2_b32 v38, v4, v5 offset0:4 offset1:5
	ds_write2_b32 v38, v6, v7 offset0:6 offset1:7
	s_waitcnt lgkmcnt(0)
	s_barrier
	ds_read2_b32 v[28:29], v39 offset1:65
	ds_read2_b32 v[30:31], v39 offset0:130 offset1:195
	ds_read2_b32 v[32:33], v40 offset1:65
	ds_read2_b32 v[34:35], v40 offset0:130 offset1:195
	s_mul_i32 s1, s7, 47663
	s_lshr_b32 s1, s1, 21
	s_mul_i32 s0, s1, 44
	s_sub_i32 s0, s7, s0
	s_mul_i32 s1, s1, 180224
	s_lshl_b32 s0, s0, 6
	s_add_i32 s1, s1, s0
	s_lshl_b32 s1, s1, 1
	s_add_u32 s40, s28, s1
	s_addc_u32 s41, s29, 0
	s_waitcnt lgkmcnt(2)
	v_cvt_pk_bf16_f32 v24, v28, v29
	v_cvt_pk_bf16_f32 v25, v30, v31
	s_waitcnt lgkmcnt(0)
	v_cvt_pk_bf16_f32 v26, v32, v33
	v_cvt_pk_bf16_f32 v27, v34, v35
	global_store_dwordx4 v37, v[24:27], s[40:41]
	s_add_i32 s7, s7, s94
	s_cmp_lt_u32 s7, 704
	s_cbranch_scc0 .Lcv_dn_end
	v_add_u32_e32 v38, 16640, v38
	v_add_u32_e32 v39, 16640, v39
	v_add_u32_e32 v40, 16640, v40
	s_lshl_b32 s5, s94, 1
	s_add_i32 s5, s5, s7
	s_cmp_lt_u32 s5, 704
	s_cbranch_scc0 .Lcv_dn_ni1
	s_mul_i32 s1, s5, 47663
	s_lshr_b32 s1, s1, 21
	s_mul_i32 s0, s1, 44
	s_sub_i32 s0, s5, s0
	s_lshl_b32 s9, s0, 16
	s_lshl_b32 s10, s1, 6
	s_add_i32 s9, s9, s10
	s_lshl_b32 s9, s9, 2
	s_add_u32 s38, s24, s9
	s_addc_u32 s39, s25, 0
	global_load_dwordx4 v[0:3], v36, s[38:39]
	global_load_dwordx4 v[4:7], v36, s[38:39] offset:16
	s_waitcnt vmcnt(4)
	s_branch .Lcv_dn_go1

.Lcv_dn_go1:
	ds_write2_b32 v38, v8, v9 offset0:0 offset1:1
	ds_write2_b32 v38, v10, v11 offset0:2 offset1:3
	ds_write2_b32 v38, v12, v13 offset0:4 offset1:5
	ds_write2_b32 v38, v14, v15 offset0:6 offset1:7
	s_waitcnt lgkmcnt(0)
	s_barrier
	ds_read2_b32 v[28:29], v39 offset1:65
	ds_read2_b32 v[30:31], v39 offset0:130 offset1:195
	ds_read2_b32 v[32:33], v40 offset1:65
	ds_read2_b32 v[34:35], v40 offset0:130 offset1:195
	s_mul_i32 s1, s7, 47663
	s_lshr_b32 s1, s1, 21
	s_mul_i32 s0, s1, 44
	s_sub_i32 s0, s7, s0
	s_mul_i32 s1, s1, 180224
	s_lshl_b32 s0, s0, 6
	s_add_i32 s1, s1, s0
	s_lshl_b32 s1, s1, 1
	s_add_u32 s40, s28, s1
	s_addc_u32 s41, s29, 0
	s_waitcnt lgkmcnt(2)
	v_cvt_pk_bf16_f32 v24, v28, v29
	v_cvt_pk_bf16_f32 v25, v30, v31
	s_waitcnt lgkmcnt(0)
	v_cvt_pk_bf16_f32 v26, v32, v33
	v_cvt_pk_bf16_f32 v27, v34, v35
	global_store_dwordx4 v37, v[24:27], s[40:41]
	s_add_i32 s7, s7, s94
	s_cmp_lt_u32 s7, 704
	s_cbranch_scc0 .Lcv_dn_end
	v_add_u32_e32 v38, 16640, v38
	v_add_u32_e32 v39, 16640, v39
	v_add_u32_e32 v40, 16640, v40
	s_lshl_b32 s5, s94, 1
	s_add_i32 s5, s5, s7
	s_cmp_lt_u32 s5, 704
	s_cbranch_scc0 .Lcv_dn_ni2
	s_mul_i32 s1, s5, 47663
	s_lshr_b32 s1, s1, 21
	s_mul_i32 s0, s1, 44
	s_sub_i32 s0, s5, s0
	s_lshl_b32 s9, s0, 16
	s_lshl_b32 s10, s1, 6
	s_add_i32 s9, s9, s10
	s_lshl_b32 s9, s9, 2
	s_add_u32 s38, s24, s9
	s_addc_u32 s39, s25, 0
	global_load_dwordx4 v[8:11], v36, s[38:39]
	global_load_dwordx4 v[12:15], v36, s[38:39] offset:16
	s_waitcnt vmcnt(4)
	s_branch .Lcv_dn_go2

.Lcv_dn_go2:
	ds_write2_b32 v38, v16, v17 offset0:0 offset1:1
	ds_write2_b32 v38, v18, v19 offset0:2 offset1:3
	ds_write2_b32 v38, v20, v21 offset0:4 offset1:5
	ds_write2_b32 v38, v22, v23 offset0:6 offset1:7
	s_waitcnt lgkmcnt(0)
	s_barrier
	ds_read2_b32 v[28:29], v39 offset1:65
	ds_read2_b32 v[30:31], v39 offset0:130 offset1:195
	ds_read2_b32 v[32:33], v40 offset1:65
	ds_read2_b32 v[34:35], v40 offset0:130 offset1:195
	s_mul_i32 s1, s7, 47663
	s_lshr_b32 s1, s1, 21
	s_mul_i32 s0, s1, 44
	s_sub_i32 s0, s7, s0
	s_mul_i32 s1, s1, 180224
	s_lshl_b32 s0, s0, 6
	s_add_i32 s1, s1, s0
	s_lshl_b32 s1, s1, 1
	s_add_u32 s40, s28, s1
	s_addc_u32 s41, s29, 0
	s_waitcnt lgkmcnt(2)
	v_cvt_pk_bf16_f32 v24, v28, v29
	v_cvt_pk_bf16_f32 v25, v30, v31
	s_waitcnt lgkmcnt(0)
	v_cvt_pk_bf16_f32 v26, v32, v33
	v_cvt_pk_bf16_f32 v27, v34, v35
	global_store_dwordx4 v37, v[24:27], s[40:41]
	s_add_i32 s7, s7, s94
	s_cmp_lt_u32 s7, 704
	s_cbranch_scc0 .Lcv_dn_end
	v_subrev_u32_e32 v38, 33280, v38
	v_subrev_u32_e32 v39, 33280, v39
	v_subrev_u32_e32 v40, 33280, v40
	s_branch .Lcv_dn_loop
.Lcv_dn_end:
	s_barrier
	s_cmp_eq_u32 s13, 0
	s_cbranch_scc1 .Lcv_ret_pro
	s_branch .Lcv_ret_row
